# on top of v3: phase-0 (layer 0) W_in transpose with gain multiply gets the same pipelined trip: 16 loads in flight with counted waits
# speedup vs baseline: 1.0157x; 1.0066x over previous
; #define ARGP(i) ((const GAS float*)ldptr(ptab, (i)))
; __device__ __forceinline__ void transpose_item(const GAS float* W, int K, int N, const GAS float* gain, GAS bf16* WT, LAS float* scr, int item, int lane, int remap) {
;     ...
; #pragma unroll 8
;     for (int i = 0; i < 32; ++i) { const int kk = 2 * i + (lane >> 5); float w = W[(size_t)(k0 + kk) * N + ns + (lane & 31)]; if (gain) w *= gain[k0 + kk]; scr[kk * 33 + (lane & 31)] = w; }
; __global__ void __launch_bounds__(512, 2) fwd(Args a) {
;     ...
;                 constexpr int I_IN = (D / 64) * (PW / 32), I_OUT = (MW / 64) * (D / 32);
;                 for (int it = c.gw; it < I_IN + I_OUT; it += c.ngw) {
;                     if (it < I_IN) transpose_item(ARGP(2), D, PW, ARGP(1), c.Wt_in, scr, it, c.lane, 1);
.LBB0_18:
	s_andn2_b64 vcc, exec, s[12:13]
	s_cbranch_vccnz .Lmy_win0_nogain
	v_lshl_add_u64 v[48:49], s[8:9], 0, v[32:33]
	v_lshl_add_u64 v[34:35], s[8:9], 0, v[16:17]
	global_load_dword v89, v[48:49], off
	v_lshl_add_u64 v[50:51], v[30:31], 0, s[10:11]
	global_load_dword v81, v[50:51], off
	v_lshl_add_u64 v[50:51], v[28:29], 0, s[10:11]
	global_load_dword v82, v[50:51], off
	v_lshl_add_u64 v[50:51], v[26:27], 0, s[10:11]
	global_load_dword v83, v[50:51], off
	v_lshl_add_u64 v[50:51], v[24:25], 0, s[10:11]
	global_load_dword v84, v[50:51], off
	v_lshl_add_u64 v[50:51], v[22:23], 0, s[10:11]
	global_load_dword v85, v[50:51], off
	v_lshl_add_u64 v[50:51], v[20:21], 0, s[10:11]
	global_load_dword v86, v[50:51], off
	v_lshl_add_u64 v[50:51], v[18:19], 0, s[10:11]
	global_load_dword v87, v[50:51], off
	v_lshl_add_u64 v[50:51], v[14:15], 0, s[10:11]
	global_load_dword v88, v[50:51], off
	global_load_dword v90, v[34:35], off offset:8
	global_load_dword v91, v[34:35], off offset:16
	global_load_dword v92, v[34:35], off offset:24
	global_load_dword v93, v[34:35], off offset:32
	global_load_dword v94, v[34:35], off offset:40
	global_load_dword v95, v[34:35], off offset:48
	global_load_dword v96, v[34:35], off offset:56
	s_waitcnt vmcnt(14)
	v_mul_f32_e32 v81, v81, v89
	ds_write_b32 v13, v81
	s_waitcnt vmcnt(6)
	v_mul_f32_e32 v82, v82, v90
	ds_write_b32 v13, v82 offset:264
	s_waitcnt vmcnt(5)
	v_mul_f32_e32 v83, v83, v91
	ds_write_b32 v13, v83 offset:528
	s_waitcnt vmcnt(4)
	v_mul_f32_e32 v84, v84, v92
	ds_write_b32 v13, v84 offset:792
	s_waitcnt vmcnt(3)
	v_mul_f32_e32 v85, v85, v93
	ds_write_b32 v13, v85 offset:1056
	s_waitcnt vmcnt(2)
	v_mul_f32_e32 v86, v86, v94
	ds_write_b32 v13, v86 offset:1320
	s_waitcnt vmcnt(1)
	v_mul_f32_e32 v87, v87, v95
	ds_write_b32 v13, v87 offset:1584
	s_waitcnt vmcnt(0)
	v_mul_f32_e32 v48, v88, v96
	s_branch .LBB0_17
